# k23: k18 + layer-1 mixer rebalance: each prompt-chain workgroup first runs sample unit 960+c, side workgroups skip units 960..1023
# speedup vs baseline: 1.0246x; 1.0033x over previous
; __device__ __forceinline__ void mixer_layer1(Frame& F) {
;     int bid = blockIdx.x; asm volatile("" : "+s"(bid));
;     if (bid < 64) { mix_hg_unit(F, bid >> 3, bid & 7, 0); return; }
; #pragma unroll 1
;     for (int u = bid - 64; u < 1024 + 8; u += F.G - 64) {
;         if (u < 1024) mix_hg_unit(F, u >> 3, u & 7, 1); else mix_hg_unit(F, 0, u - 1024, 2);
;     }
; }
.LBB0_847:
	s_andn2_b64 vcc, exec, s[0:1]
	s_cbranch_vccnz .LBB0_898
	s_mov_b32 s0, s42
	s_mov_b64 s[4:5], -1
	s_cmpk_gt_u32 s0, 0x447
	s_cbranch_scc1 .LBB0_874
	s_waitcnt vmcnt(0) lgkmcnt(0)
	v_ashrrev_i32_e32 v4, 7, v145
	v_ashrrev_i32_e32 v5, 31, v4
	v_readlane_b32 s10, v253, 19
	s_movk_i32 s1, 0x80
	v_cmp_gt_i32_e64 s[8:9], 1, v4
	v_lshlrev_b64 v[4:5], 12, v[4:5]
	v_and_b32_e32 v6, 0x7f, v145
	v_readlane_b32 s11, v253, 20
	v_and_b32_e32 v1, 7, v145
	v_cmp_gt_i32_e64 s[4:5], s1, v145
	s_movk_i32 s1, 0x7f
	v_lshlrev_b32_e32 v9, 2, v145
	v_lshl_add_u64 v[4:5], s[10:11], 0, v[4:5]
	v_lshlrev_b32_e32 v2, 2, v6
	v_cmp_lt_i32_e64 s[6:7], s1, v145
	v_lshlrev_b32_e32 v106, 4, v1
	v_lshl_add_u64 v[4:5], v[4:5], 0, v[2:3]
	v_and_b32_e32 v2, 4, v9
	s_movk_i32 s1, 0x60
	v_ashrrev_i32_e32 v0, 3, v145
	v_and_or_b32 v2, v106, s1, v2
	s_movk_i32 s12, 0x110
	v_lshlrev_b32_e32 v107, 1, v2
	v_mul_lo_u32 v2, v0, s12
	s_movk_i32 s15, 0x210
	v_lshrrev_b32_e32 v8, 4, v190
	v_readlane_b32 s13, v253, 62
	v_add_u32_e32 v108, 0, v2
	v_lshlrev_b32_e32 v94, 5, v1
	v_mul_lo_u32 v2, v0, s15
	v_lshlrev_b32_e32 v1, 6, v1
	v_readlane_b32 s14, v253, 63
	s_mov_b64 s[10:11], 0x440000
	v_readlane_b32 s25, v254, 7
	v_add3_u32 v110, s14, v2, v1
	v_add_u32_e32 v111, s13, v1
	v_lshlrev_b32_e32 v1, 2, v8
	v_add_u32_e32 v104, s13, v9
	v_lshl_add_u64 v[92:93], v[4:5], 0, s[10:11]
	v_add_u32_e32 v109, s25, v9
	v_or_b32_e32 v4, 3, v1
	v_mov_b32_e32 v9, 0xfffffdf0
	v_and_b32_e32 v7, 15, v145
	v_readlane_b32 s10, v252, 57
	s_and_b32 s1, s47, 0xffffffc0
	v_mad_u32_u24 v115, v4, s15, v9
	v_bfe_u32 v9, v145, 2, 2
	v_mov_b32_e32 v95, v3
	v_readlane_b32 s11, v252, 58
	s_add_i32 s1, s1, s14
	v_or_b32_e32 v5, 2, v1
	v_or_b32_e32 v9, v1, v9
	v_cmp_lt_u32_e64 s[14:15], v1, v7
	v_cmp_gt_u32_e64 s[16:17], v1, v7
	v_ashrrev_i32_e32 v1, 31, v0
	v_lshl_add_u64 v[96:97], s[10:11], 0, v[94:95]
	v_mad_u32_u24 v95, v7, s12, 0
	v_mul_u32_u24_e32 v114, 0x210, v4
	v_mad_u32_u24 v9, v9, s12, 0
	v_cmp_gt_u32_e64 s[10:11], v4, v7
	v_cmp_gt_u32_e64 s[12:13], v5, v7
	v_lshlrev_b64 v[4:5], 11, v[0:1]
	v_lshl_add_u64 v[4:5], v[96:97], 0, v[4:5]
	s_mov_b64 s[22:23], 0x2200000
	v_lshl_add_u64 v[98:99], v[4:5], 0, s[22:23]
	s_lshl_b32 s22, s46, 4
	s_ashr_i32 s23, s22, 31
	s_mov_b32 s43, s71
	v_readlane_b32 s56, v251, 5
	s_sub_i32 s24, s0, 64
	s_mov_b32 s100, s87
	s_movk_i32 s101, 0x407
	s_cmp_gt_i32 s0, 63
	s_cbranch_scc1 .Lmx1_side
	s_add_i32 s24, s0, 0x3c0
	s_movk_i32 s100, 64
	s_movk_i32 s101, 0x3ff
.Lmx1_side:
	s_lshl_b64 s[26:27], s[22:23], 2
	v_readlane_b32 s68, v251, 17
	v_readlane_b32 s69, v251, 18
	s_add_u32 s22, s68, s26
	v_lshlrev_b32_e32 v2, 2, v7
	s_addc_u32 s23, s69, s27
	v_lshlrev_b32_e32 v105, 13, v0
	v_add_u32_e32 v113, s1, v2
	v_lshlrev_b32_e32 v10, 3, v145
	v_lshl_add_u64 v[4:5], s[22:23], 0, v[2:3]
	v_and_b32_e32 v1, 48, v190
	v_cmp_gt_i32_e64 s[22:23], 8, v0
	v_readlane_b32 s1, v253, 23
	v_and_b32_e32 v118, 24, v10
	v_cmp_gt_i32_e64 s[18:19], 16, v0
	v_cmp_lt_i32_e64 s[20:21], 15, v0
	v_readlane_b32 s62, v251, 11
	v_readlane_b32 s63, v251, 12
	v_readlane_b32 s64, v251, 13
	v_readlane_b32 s65, v251, 14
	v_add_u32_e32 v119, s25, v1
	v_lshlrev_b32_e32 v2, 4, v7
	v_cndmask_b32_e64 v120, 0, v0, s[22:23]
	s_add_u32 s1, s1, s26
	v_readlane_b32 s25, v253, 24
	v_lshl_add_u32 v0, s0, 8, v105
	v_readlane_b32 s66, v251, 15
	v_readlane_b32 s67, v251, 16
	v_readlane_b32 s71, v251, 20
	v_readlane_b32 s64, v252, 3
	v_readlane_b32 s62, v253, 29
	v_lshlrev_b32_e32 v1, 1, v118
	v_or_b32_e32 v7, 0xc0, v2
	v_or_b32_e32 v10, 0xc8, v2
	s_addc_u32 s38, s25, s27
	v_lshlrev_b32_e32 v2, 11, v8
	s_lshl_b32 s25, s0, 7
	v_or_b32_e32 v0, v0, v94
	v_and_b32_e32 v112, 48, v145
	v_mul_u32_u24_e32 v116, 0x840, v8
	v_lshl_add_u32 v117, s46, 5, v9
	v_readlane_b32 s65, v252, 4
	v_readlane_b32 s66, v254, 30
	s_mov_b32 s71, s43
	v_readlane_b32 s63, v253, 30
	v_lshl_add_u64 v[100:101], v[4:5], 0, v[2:3]
	s_add_i32 s26, s25, 0xfffde000
	s_cmp_gt_i32 s0, 63
	s_cbranch_scc1 .Lmx1_side2
	s_add_i32 s26, s25, 0xffffe000
.Lmx1_side2:
	v_add_u32_e32 v121, 0xfffbc000, v0
	v_lshlrev_b32_e32 v122, 2, v6
	v_add_u32_e32 v123, v9, v1
	v_add_u32_e32 v124, v9, v7
	v_add_u32_e32 v125, v9, v10
	v_readlane_b32 s57, v251, 6
	v_readlane_b32 s58, v251, 7
	v_readlane_b32 s59, v251, 8
	v_readlane_b32 s60, v251, 9
	v_readlane_b32 s61, v251, 10
	v_readlane_b32 s70, v251, 19
	v_readlane_b32 s67, v254, 31
	s_branch .LBB0_853

; __device__ __forceinline__ void mixer_layer1(Frame& F) {
;     ...
; #pragma unroll 1
;     for (int u = bid - 64; u < 1024 + 8; u += F.G - 64) {
;         if (u < 1024) mix_hg_unit(F, u >> 3, u & 7, 1); else mix_hg_unit(F, 0, u - 1024, 2);
;     }
.LBB0_852:
	v_readlane_b32 s25, v253, 50
	s_add_i32 s26, s26, s25
	s_add_i32 s24, s24, s100
	v_readlane_b32 s25, v253, 51
	s_cmp_gt_i32 s24, s101
	s_nop 0
	v_add_u32_e32 v121, s25, v121
	s_cbranch_scc1 .LBB0_874
.LBB0_853:
	s_cmp_lt_i32 s0, 64
	s_cbranch_scc1 .Lmx1_go
	s_cmpk_lt_i32 s24, 0x3c0
	s_cbranch_scc1 .Lmx1_go
	s_cmpk_gt_i32 s24, 0x3ff
	s_cbranch_scc0 .LBB0_852

; __device__ __forceinline__ void mixer_layer1(Frame& F) {
;     ...
;     if (bid < 64) { mix_hg_unit(F, bid >> 3, bid & 7, 0); return; }
; #pragma unroll 1
;     for (int u = bid - 64; u < 1024 + 8; u += F.G - 64) {
;         if (u < 1024) mix_hg_unit(F, u >> 3, u & 7, 1); else mix_hg_unit(F, 0, u - 1024, 2);
;     }
; }
.LBB0_874:
	s_cmp_lt_i32 s0, 64
	s_cselect_b64 s[4:5], -1, 0

; __global__ void __launch_bounds__(NWAVES * 64, 2) fwd_kernel(Args args) {
	.amdhsa_kernel _Z10fwd_kernel4Args
		.amdhsa_group_segment_fixed_size 0
		.amdhsa_private_segment_fixed_size 0
		.amdhsa_kernarg_size 488
		.amdhsa_user_sgpr_count 2
		.amdhsa_user_sgpr_dispatch_ptr 0
		.amdhsa_user_sgpr_queue_ptr 0
		.amdhsa_user_sgpr_kernarg_segment_ptr 1
		.amdhsa_user_sgpr_dispatch_id 0
		.amdhsa_user_sgpr_kernarg_preload_length 0
		.amdhsa_user_sgpr_kernarg_preload_offset 0
		.amdhsa_user_sgpr_private_segment_size 0
		.amdhsa_uses_dynamic_stack 0
		.amdhsa_enable_private_segment 0
		.amdhsa_system_sgpr_workgroup_id_x 1
		.amdhsa_system_sgpr_workgroup_id_y 0
		.amdhsa_system_sgpr_workgroup_id_z 0
		.amdhsa_system_sgpr_workgroup_info 0
		.amdhsa_system_vgpr_workitem_id 2
		.amdhsa_next_free_vgpr 256
		.amdhsa_next_free_sgpr 102
		.amdhsa_accum_offset 256
		.amdhsa_reserve_vcc 1
		.amdhsa_float_round_mode_32 0
		.amdhsa_float_round_mode_16_64 0
		.amdhsa_float_denorm_mode_32 3
		.amdhsa_float_denorm_mode_16_64 3
		.amdhsa_dx10_clamp 1
		.amdhsa_ieee_mode 1
		.amdhsa_fp16_overflow 0
		.amdhsa_tg_split 0
		.amdhsa_exception_fp_ieee_invalid_op 0
		.amdhsa_exception_fp_denorm_src 0
		.amdhsa_exception_fp_ieee_div_zero 0
		.amdhsa_exception_fp_ieee_overflow 0
		.amdhsa_exception_fp_ieee_underflow 0
		.amdhsa_exception_fp_ieee_inexact 0
		.amdhsa_exception_int_div_zero 0
	.end_amdhsa_kernel

; __global__ void __launch_bounds__(NWAVES * 64, 2) fwd_kernel(Args args) {
amdhsa.kernels:
  - .agpr_count:     0
    .args:
      - .offset:         0
        .size:           232
        .value_kind:     by_value
      - .offset:         232
        .size:           4
        .value_kind:     hidden_block_count_x
      - .offset:         236
        .size:           4
        .value_kind:     hidden_block_count_y
      - .offset:         240
        .size:           4
        .value_kind:     hidden_block_count_z
      - .offset:         244
        .size:           2
        .value_kind:     hidden_group_size_x
      - .offset:         246
        .size:           2
        .value_kind:     hidden_group_size_y
      - .offset:         248
        .size:           2
        .value_kind:     hidden_group_size_z
      - .offset:         250
        .size:           2
        .value_kind:     hidden_remainder_x
      - .offset:         252
        .size:           2
        .value_kind:     hidden_remainder_y
      - .offset:         254
        .size:           2
        .value_kind:     hidden_remainder_z
      - .offset:         272
        .size:           8
        .value_kind:     hidden_global_offset_x
      - .offset:         280
        .size:           8
        .value_kind:     hidden_global_offset_y
      - .offset:         288
        .size:           8
        .value_kind:     hidden_global_offset_z
      - .offset:         296
        .size:           2
        .value_kind:     hidden_grid_dims
      - .offset:         320
        .size:           8
        .value_kind:     hidden_multigrid_sync_arg
      - .offset:         352
        .size:           4
        .value_kind:     hidden_dynamic_lds_size
    .group_segment_fixed_size: 0
    .kernarg_segment_align: 8
    .kernarg_segment_size: 488
    .language:       OpenCL C
    .language_version:
      - 2
      - 0
    .max_flat_workgroup_size: 512
    .name:           _Z10fwd_kernel4Args
    .private_segment_fixed_size: 0
    .sgpr_count:     108
    .sgpr_spill_count: 358
    .symbol:         _Z10fwd_kernel4Args.kd
    .uniform_work_group_size: 1
    .uses_dynamic_stack: false
    .vgpr_count:     256
    .vgpr_spill_count: 0
    .wavefront_size: 64
